# gdn chain loader steady-state pacing halved (s_sleep 2 -> 1) on top of the paced gla loader
# baseline (speedup 1.0000x reference)
; #define LBAR() do { asm volatile("s_waitcnt lgkmcnt(0)" ::: "memory"); __builtin_amdgcn_s_barrier(); asm volatile("" ::: "memory"); } while (0)
; #define WAITV(N_) asm volatile("s_waitcnt vmcnt(" #N_ ")" ::: "memory")
; #define ISSUE_XG(s_) do { const unsigned char* g_ = A.blob + (unit0 + CHUNK_OF(s_)) * BLOB + lane * 16; const unsigned l_ = lds0 + ((s_) & 1) * C_BUF; \
;         _Pragma("unroll") for (int k = 0; k < 8; ++k) { const unsigned o_ = (lw + 4 * k) * 1024; DMA1(g_ + o_, l_ + o_); __builtin_amdgcn_s_sleep(LOADER_PACE); } } while (0)
; #define WAITV(N_) asm volatile("s_waitcnt vmcnt(" #N_ ")" ::: "memory")
; #define ISSUE_XG(s_) do { const unsigned char* g_ = A.blobA + (unit0 + CHUNK_OF(s_)) * BLOBA + qo + lane * 16; const unsigned l_ = lds0 + ((s_) & 1) * CB_BUF; \
;         _Pragma("unroll") for (int k = 0; k < 4; ++k) { const unsigned o_ = (lw + 4 * k) * 1024; DMA1(g_ + o_, l_ + o_); } } while (0)
; __device__ __forceinline__ void gdn_chain_unit(LAS unsigned char* lds, const GdnChainArgs& A, int item, int half) {
;     ...
;         if (!(flags & 4)) { ISSUE_XG(0); ISSUE_YG(0); ISSUE_XG(1); }
;         WAITV(0);
;         LBAR();
;         for (int s = 0; s < NCH; ++s) {
;             if (s + 1 < NCH && !(flags & 4)) ISSUE_YG(s + 1);
;             LBAR();
;             if (s + 2 < NCH && !(flags & 4)) ISSUE_XG(s + 2);
;             if (s <= NCH - 3 && !probe) WAITV(8); else WAITV(0);
;             LBAR();
;         }
.LBB0_661:
	v_readlane_b32 vcc_lo, v254, 44
	s_add_i32 s81, s80, 2
	s_add_i32 s78, s78, -1
	v_readlane_b32 vcc_hi, v254, 45
	s_and_b64 s[82:83], vcc, exec
	s_cselect_b32 s81, s81, s78
	v_readlane_b32 s94, v254, 46
	v_readlane_b32 s95, v254, 47
	s_add_u32 s81, s94, s81
	s_addc_u32 s82, s95, 0
	s_mul_i32 s84, s82, 0x18800
	v_mad_u64_u32 v[4:5], s[82:83], s81, v172, v[2:3]
	s_bitcmp1_b32 s80, 0
	v_add_u32_e32 v5, s84, v5
	s_cselect_b32 s80, s76, 0
	s_waitcnt lgkmcnt(0)
	s_barrier
	v_lshl_add_u64 v[6:7], v[4:5], 0, s[34:35]
	s_add_i32 s81, s80, s34
	s_mov_b32 m0, s81
	s_nop 0
	global_load_lds_dwordx4 v[6:7], off
	v_lshl_add_u64 v[6:7], v[4:5], 0, s[4:5]
	s_add_i32 s81, s80, s4
	s_sleep 1
	s_mov_b32 m0, s81
	s_nop 0
	global_load_lds_dwordx4 v[6:7], off
	v_lshl_add_u64 v[6:7], v[4:5], 0, s[6:7]
	s_add_i32 s81, s80, s6
	s_sleep 1
	s_mov_b32 m0, s81
	s_nop 0
	global_load_lds_dwordx4 v[6:7], off
	v_lshl_add_u64 v[6:7], v[4:5], 0, s[36:37]
	s_add_i32 s81, s80, s36
	s_sleep 1
	s_mov_b32 m0, s81
	s_nop 0
	global_load_lds_dwordx4 v[6:7], off
	v_lshl_add_u64 v[6:7], v[4:5], 0, s[38:39]
	s_add_i32 s81, s80, s38
	s_sleep 1
	s_mov_b32 m0, s81
	s_nop 0
	global_load_lds_dwordx4 v[6:7], off
	v_lshl_add_u64 v[6:7], v[4:5], 0, s[40:41]
	s_add_i32 s81, s80, s40
	s_sleep 1
	s_mov_b32 m0, s81
	s_nop 0
	global_load_lds_dwordx4 v[6:7], off
	s_sleep 1
	v_lshl_add_u64 v[6:7], v[4:5], 0, s[42:43]
	s_add_i32 s81, s80, s42
	s_mov_b32 m0, s81
	s_nop 0
	global_load_lds_dwordx4 v[6:7], off
	s_sleep 1
	v_lshl_add_u64 v[4:5], v[4:5], 0, s[44:45]
	s_add_i32 s80, s80, s44
	s_mov_b32 m0, s80
	s_nop 0
	global_load_lds_dwordx4 v[4:5], off
	s_sleep 1
	s_waitcnt vmcnt(8)
	s_waitcnt lgkmcnt(0)
	s_barrier
	s_cmp_eq_u32 s78, 0
	s_mov_b32 s80, s79
	s_cbranch_scc1 .LBB0_664
.LBB0_662:
	s_add_i32 s79, s80, 1
	s_and_b64 s[2:3], vcc, exec
	s_cselect_b32 s2, s79, s78
	s_add_u32 s2, s94, s2
	s_addc_u32 s3, s95, 0
	s_mul_i32 s81, s3, 0x18800
	v_mad_u64_u32 v[4:5], s[2:3], s2, v172, v[2:3]
	s_bitcmp1_b32 s79, 0
	v_add_u32_e32 v5, s81, v5
	s_cselect_b32 s81, s76, 0
	v_lshl_add_u64 v[6:7], v[4:5], 0, s[46:47]
	s_add_i32 s2, s81, s46
	s_mov_b32 m0, s2
	s_nop 0
	global_load_lds_dwordx4 v[6:7], off
	v_lshl_add_u64 v[6:7], v[4:5], 0, s[48:49]
	s_add_i32 s2, s81, s48
	s_sleep 1
	s_mov_b32 m0, s2
	s_nop 0
	global_load_lds_dwordx4 v[6:7], off
	v_lshl_add_u64 v[6:7], v[4:5], 0, s[50:51]
	s_add_i32 s2, s81, s50
	s_sleep 1
	s_mov_b32 m0, s2
	s_nop 0
	global_load_lds_dwordx4 v[6:7], off
	v_lshl_add_u64 v[6:7], v[4:5], 0, s[52:53]
	s_add_i32 s2, s81, s52
	s_sleep 1
	s_mov_b32 m0, s2
	s_nop 0
	global_load_lds_dwordx4 v[6:7], off
	v_lshl_add_u64 v[6:7], v[4:5], 0, s[54:55]
	s_add_i32 s2, s81, s67
	s_sleep 1
	s_mov_b32 m0, s2
	s_nop 0
	global_load_lds_dwordx4 v[6:7], off
	v_lshl_add_u64 v[6:7], v[4:5], 0, s[56:57]
	s_add_i32 s2, s81, s72
	s_sleep 1
	s_mov_b32 m0, s2
	s_nop 0
	global_load_lds_dwordx4 v[6:7], off
	v_lshl_add_u64 v[6:7], v[4:5], 0, s[58:59]
	s_add_i32 s2, s81, s73
	s_sleep 1
	s_mov_b32 m0, s2
	s_nop 0
	global_load_lds_dwordx4 v[6:7], off
	s_sleep 1
	v_lshl_add_u64 v[6:7], v[4:5], 0, s[60:61]
	s_add_i32 s2, s81, s74
	s_mov_b32 m0, s2
	s_nop 0
	global_load_lds_dwordx4 v[6:7], off
	v_cndmask_b32_e64 v6, 0, 1, s[64:65]
	v_cmp_ne_u32_e64 s[2:3], 1, v6
	s_andn2_b64 vcc, exec, s[64:65]
	s_sleep 1
	s_cbranch_vccnz .LBB0_661
	s_add_i32 s81, s77, s81
	v_lshl_add_u64 v[4:5], v[4:5], 0, s[62:63]
	s_mov_b32 m0, s81
	s_nop 0
	global_load_lds_dwordx4 v[4:5], off
	s_sleep 1
	s_branch .LBB0_661
.LBB0_664:
	v_readlane_b32 s4, v252, 41
	v_readlane_b32 s5, v252, 42
	s_add_i32 s67, s67, s76
	s_add_i32 s72, s72, s76
	v_lshl_add_u64 v[2:3], v[2:3], 0, s[4:5]
	v_lshl_add_u64 v[4:5], v[2:3], 0, s[46:47]
	s_add_i32 s4, s46, s76
	s_mov_b32 m0, s4
	s_nop 0
	global_load_lds_dwordx4 v[4:5], off
	v_lshl_add_u64 v[4:5], v[2:3], 0, s[48:49]
	s_sleep 1
	s_add_i32 s4, s48, s76
	s_mov_b32 m0, s4
	s_nop 0
	global_load_lds_dwordx4 v[4:5], off
	v_lshl_add_u64 v[4:5], v[2:3], 0, s[50:51]
	s_sleep 1
	s_add_i32 s4, s50, s76
	s_mov_b32 m0, s4
	s_nop 0
	global_load_lds_dwordx4 v[4:5], off
	v_lshl_add_u64 v[4:5], v[2:3], 0, s[52:53]
	s_sleep 1
	s_add_i32 s4, s52, s76
	s_mov_b32 m0, s4
	s_nop 0
	global_load_lds_dwordx4 v[4:5], off
	v_lshl_add_u64 v[4:5], v[2:3], 0, s[54:55]
	s_sleep 1
	s_mov_b32 m0, s67
	s_nop 0
	global_load_lds_dwordx4 v[4:5], off
	v_lshl_add_u64 v[4:5], v[2:3], 0, s[56:57]
	s_sleep 1
	s_mov_b32 m0, s72
	s_nop 0
	global_load_lds_dwordx4 v[4:5], off
	v_lshl_add_u64 v[4:5], v[2:3], 0, s[58:59]
	s_sleep 1
	s_add_i32 s73, s73, s76
	s_mov_b32 m0, s73
	s_nop 0
	global_load_lds_dwordx4 v[4:5], off
	s_sleep 1
	v_lshl_add_u64 v[4:5], v[2:3], 0, s[60:61]
	s_add_i32 s74, s74, s76
	s_mov_b32 m0, s74
	s_nop 0
	global_load_lds_dwordx4 v[4:5], off
	s_and_b64 vcc, exec, s[2:3]
	s_sleep 1
	s_cbranch_vccnz .LBB0_666
	s_add_i32 s2, s75, 0
	s_add_i32 s2, s2, 0x18800
	v_lshl_add_u64 v[2:3], v[2:3], 0, s[62:63]
	s_mov_b32 m0, s2
	s_nop 0
	global_load_lds_dwordx4 v[2:3], off
	s_sleep 1
